# four dependency-free grid barriers skipped; the seam after phase 0 takes the XCD-hierarchical barrier instead of cooperative-groups grid sync
# speedup vs baseline: 1.0040x; 1.0033x over previous
; __global__ void __launch_bounds__(NT_THREADS) k_mega(Params p) {
;     ...
;     if (ph + 1 < NPHASES) { if (ph == 0) grid.sync(); else xcd_barrier(xb); }
.LBB0_538:
	s_cmp_lg_u32 s81, 0x63
	s_mov_b64 s[0:1], -1
	s_cselect_b64 s[4:5], -1, 0
	s_andn2_b64 vcc, exec, s[4:5]
	s_mov_b64 s[4:5], 0
	s_cbranch_vccz .LBB0_526
